# v66 + FFN1 (s8): the tiles of the partly filled last round (nwg mod 256) are each split into two 128-row half units on two workgroups; SwiGLU epilogue stores of the unused half exec-masked
# speedup vs baseline: 1.0063x; 1.0002x over previous
.LBB0_39:
	s_add_i32 s20, s20, 1
	v_readlane_b32 s6, v252, 26
	v_readlane_b32 s8, v252, 9
	s_mul_i32 s6, s20, s6
	s_mul_hi_u32 s7, s20, s8
	s_add_i32 s7, s7, s6
	s_mul_i32 s6, s20, s8
	s_add_u32 s6, s6, s9
	v_readlane_b32 s8, v252, 25
	s_addc_u32 s7, s7, s8
	s_and_b32 s100, s2, 0xff
	s_add_u32 s100, s2, s100
	s_mov_b32 s101, s3
	v_mov_b64_e32 v[0:1], s[100:101]
	v_cmp_ge_i64_e32 vcc, s[6:7], v[0:1]
	v_cmp_lt_i64_e64 s[40:41], s[6:7], v[0:1]
	s_cbranch_vccnz .LBB0_44
	s_and_b32 s100, s2, 0xff
	s_sub_i32 s100, s2, s100
	s_sub_i32 s101, s6, s100
	s_cmp_ge_i32 s101, 0
	s_cbranch_scc0 .Lffn1_nosplit
	s_lshr_b32 s6, s101, 1
	s_add_i32 s6, s6, s100
	s_and_b32 s100, s101, 1
	s_mov_b32 s101, 1
	s_branch .Lffn1_join
.Lffn1_nosplit:
	s_mov_b32 s100, 0
	s_mov_b32 s101, 0
.Lffn1_join:
	s_cmp_gt_i32 s2, s6
	s_mov_b64 s[8:9], -1
	s_cbranch_scc1 .LBB0_42
	s_sub_i32 s7, s6, s2
	s_mul_hi_u32 s8, s7, 0xba2e8ba3
	s_lshr_b32 s8, s8, 4
	s_add_i32 s34, s8, 0x80
	s_mul_i32 s8, s8, 22
	s_sub_i32 s30, s7, s8
	s_mov_b64 s[8:9], 0
.LBB0_42:
	s_andn2_b64 vcc, exec, s[8:9]
	s_mov_b32 s21, 1
	s_cbranch_vccnz .LBB0_44
	s_ashr_i32 s7, s6, 31
	s_lshr_b32 s7, s7, 29
	s_add_i32 s7, s6, s7
	s_ashr_i32 s8, s7, 3
	s_and_b32 s7, s7, -8
	s_sub_i32 s6, s6, s7
	s_lshr_b32 s7, s6, 31
	v_readlane_b32 s9, v255, 32
	s_or_b32 s7, s9, s7
	s_mul_i32 s6, s7, s6
	s_add_i32 s6, s6, s8
	s_mul_hi_i32 s7, s6, 0x2e8ba2e9
	s_lshr_b32 s8, s7, 31
	s_ashr_i32 s7, s7, 5
	s_add_i32 s7, s7, s8
	s_lshl_b32 s8, s7, 3
	v_readlane_b32 s9, v255, 18
	s_sub_i32 s9, s9, s8
	s_min_i32 s9, s9, 8
	s_abs_i32 s11, s9
	v_cvt_f32_u32_e32 v0, s11
	s_sub_i32 s13, 0, s11
	s_mulk_i32 s7, 0xb0
	s_sub_i32 s6, s6, s7
	v_rcp_iflag_f32_e32 v0, v0
	s_abs_i32 s7, s6
	s_xor_b32 s12, s6, s9
	s_ashr_i32 s12, s12, 31
	v_mul_f32_e32 v0, 0x4f7ffffe, v0
	v_cvt_u32_f32_e32 v0, v0
	s_mov_b32 s21, 0
	v_readfirstlane_b32 s18, v0
	s_mul_i32 s13, s13, s18
	s_mul_hi_u32 s13, s18, s13
	s_add_i32 s18, s18, s13
	s_mul_hi_u32 s13, s7, s18
	s_mul_i32 s18, s13, s11
	s_sub_i32 s7, s7, s18
	s_add_i32 s18, s13, 1
	s_sub_i32 s19, s7, s11
	s_cmp_ge_u32 s7, s11
	s_cselect_b32 s13, s18, s13
	s_cselect_b32 s7, s19, s7
	s_add_i32 s18, s13, 1
	s_cmp_ge_u32 s7, s11
	s_cselect_b32 s7, s18, s13
	s_xor_b32 s7, s7, s12
	s_sub_i32 s30, s7, s12
	s_mul_i32 s7, s30, s9
	s_sub_i32 s6, s6, s7
	s_add_i32 s6, s6, s8
	s_lshl_b32 s34, s6, 1
	s_add_i32 s34, s34, s100
	s_mov_b32 s21, s101

.LBB0_52:
	v_mul_f32_e32 v128, 0xbfb8aa3b, v124
	v_exp_f32_e32 v129, v128
	v_mul_f32_e32 v128, 0xbfb8aa3b, v125
	v_exp_f32_e32 v131, v128
	v_readlane_b32 s4, v255, 28
	v_add_f32_e32 v129, 1.0, v129
	v_rcp_f32_e32 v130, v129
	v_add_f32_e32 v129, 1.0, v131
	v_rcp_f32_e32 v131, v129
	v_lshl_or_b32 v128, s44, 7, v222
	s_lshl_b32 s0, s42, 7
	v_readlane_b32 s5, v255, 29
	v_pk_mul_f32 v[124:125], v[124:125], v[130:131]
	v_mul_f32_e32 v130, 0xbfb8aa3b, v126
	v_mul_f32_e32 v131, 0xbfb8aa3b, v127
	v_exp_f32_e32 v130, v130
	v_exp_f32_e32 v131, v131
	v_pk_mul_f32 v[116:117], v[116:117], v[124:125]
	v_ashrrev_i32_e32 v129, 31, v128
	v_add_f32_e32 v124, 1.0, v130
	v_add_f32_e32 v125, 1.0, v131
	v_mul_f32_e32 v130, 0xbfb8aa3b, v120
	v_mul_f32_e32 v131, 0xbfb8aa3b, v121
	v_rcp_f32_e32 v124, v124
	v_rcp_f32_e32 v125, v125
	v_exp_f32_e32 v130, v130
	v_exp_f32_e32 v131, v131
	v_cvt_pk_bf16_f32 v116, v116, v117
	v_pk_mul_f32 v[124:125], v[126:127], v[124:125]
	v_add_f32_e32 v126, 1.0, v130
	v_add_f32_e32 v127, 1.0, v131
	v_mul_f32_e32 v130, 0xbfb8aa3b, v122
	v_mul_f32_e32 v131, 0xbfb8aa3b, v123
	v_exp_f32_e32 v130, v130
	v_exp_f32_e32 v131, v131
	v_rcp_f32_e32 v126, v126
	v_rcp_f32_e32 v127, v127
	v_add_f32_e32 v130, 1.0, v130
	v_add_f32_e32 v131, 1.0, v131
	v_rcp_f32_e32 v130, v130
	v_rcp_f32_e32 v131, v131
	v_pk_mul_f32 v[120:121], v[120:121], v[126:127]
	v_pk_mul_f32 v[118:119], v[118:119], v[124:125]
	v_pk_mul_f32 v[112:113], v[112:113], v[120:121]
	v_pk_mul_f32 v[120:121], v[122:123], v[130:131]
	v_cvt_pk_bf16_f32 v117, v118, v119
	v_pk_mul_f32 v[114:115], v[114:115], v[120:121]
	v_add_u32_e32 v132, s0, v202
	v_cvt_pk_bf16_f32 v119, v114, v115
	v_mul_f32_e32 v114, 0xbfb8aa3b, v108
	v_exp_f32_e32 v122, v114
	v_mul_f32_e32 v114, 0xbfb8aa3b, v109
	v_exp_f32_e32 v123, v114
	v_cvt_pk_bf16_f32 v118, v112, v113
	v_mov_b64_e32 v[112:113], s[4:5]
	s_movk_i32 s6, 0x1600
	v_mad_i64_i32 v[120:121], s[4:5], v132, s6, v[112:113]
	v_lshlrev_b64 v[114:115], 1, v[128:129]
	v_add_f32_e32 v122, 1.0, v122
	v_add_f32_e32 v123, 1.0, v123
	v_lshl_add_u64 v[120:121], v[120:121], 0, v[114:115]
	v_rcp_f32_e32 v122, v122
	v_rcp_f32_e32 v123, v123
	global_store_dwordx4 v[120:121], v[116:119], off
	s_andn2_b64 vcc, exec, s[40:41]
	v_readlane_b32 s9, v252, 8
	v_mul_f32_e32 v116, 0xbfb8aa3b, v110
	v_mul_f32_e32 v117, 0xbfb8aa3b, v111
	v_exp_f32_e32 v116, v116
	v_exp_f32_e32 v117, v117
	v_pk_mul_f32 v[108:109], v[108:109], v[122:123]
	v_or_b32_e32 v118, 16, v132
	v_pk_mul_f32 v[100:101], v[100:101], v[108:109]
	v_add_f32_e32 v108, 1.0, v116
	v_add_f32_e32 v109, 1.0, v117
	v_mul_f32_e32 v116, 0xbfb8aa3b, v104
	v_mul_f32_e32 v117, 0xbfb8aa3b, v105
	v_rcp_f32_e32 v108, v108
	v_rcp_f32_e32 v109, v109
	v_exp_f32_e32 v116, v116
	v_exp_f32_e32 v117, v117
	s_mov_b32 s54, 0x30c30c31
	v_pk_mul_f32 v[108:109], v[110:111], v[108:109]
	v_add_f32_e32 v110, 1.0, v116
	v_add_f32_e32 v111, 1.0, v117
	v_mul_f32_e32 v116, 0xbfb8aa3b, v106
	v_mul_f32_e32 v117, 0xbfb8aa3b, v107
	v_exp_f32_e32 v116, v116
	v_exp_f32_e32 v117, v117
	v_rcp_f32_e32 v110, v110
	v_rcp_f32_e32 v111, v111
	v_add_f32_e32 v116, 1.0, v116
	v_add_f32_e32 v117, 1.0, v117
	v_rcp_f32_e32 v116, v116
	v_rcp_f32_e32 v117, v117
	v_pk_mul_f32 v[104:105], v[104:105], v[110:111]
	v_pk_mul_f32 v[102:103], v[102:103], v[108:109]
	v_pk_mul_f32 v[104:105], v[96:97], v[104:105]
	v_pk_mul_f32 v[96:97], v[106:107], v[116:117]
	s_movk_i32 s64, 0xa8
	v_pk_mul_f32 v[106:107], v[98:99], v[96:97]
	v_cvt_pk_bf16_f32 v96, v100, v101
	v_mul_f32_e32 v100, 0xbfb8aa3b, v92
	v_cvt_pk_bf16_f32 v97, v102, v103
	v_exp_f32_e32 v102, v100
	v_mul_f32_e32 v100, 0xbfb8aa3b, v93
	v_exp_f32_e32 v103, v100
	v_mad_i64_i32 v[100:101], s[4:5], v118, s6, v[112:113]
	v_cvt_pk_bf16_f32 v98, v104, v105
	v_cvt_pk_bf16_f32 v99, v106, v107
	v_add_f32_e32 v102, 1.0, v102
	v_add_f32_e32 v103, 1.0, v103
	v_lshl_add_u64 v[100:101], v[100:101], 0, v[114:115]
	v_rcp_f32_e32 v102, v102
	v_rcp_f32_e32 v103, v103
	global_store_dwordx4 v[100:101], v[96:99], off
	v_pk_mul_f32 v[92:93], v[92:93], v[102:103]
	s_nop 0
	v_mul_f32_e32 v96, 0xbfb8aa3b, v94
	v_mul_f32_e32 v97, 0xbfb8aa3b, v95
	v_exp_f32_e32 v96, v96
	v_exp_f32_e32 v97, v97
	v_pk_mul_f32 v[84:85], v[84:85], v[92:93]
	v_or_b32_e32 v98, 32, v132
	v_add_f32_e32 v92, 1.0, v96
	v_add_f32_e32 v93, 1.0, v97
	v_mul_f32_e32 v96, 0xbfb8aa3b, v88
	v_mul_f32_e32 v97, 0xbfb8aa3b, v89
	v_rcp_f32_e32 v92, v92
	v_rcp_f32_e32 v93, v93
	v_exp_f32_e32 v96, v96
	v_exp_f32_e32 v97, v97
	v_pk_mul_f32 v[92:93], v[94:95], v[92:93]
	v_add_f32_e32 v94, 1.0, v96
	v_add_f32_e32 v95, 1.0, v97
	v_mul_f32_e32 v96, 0xbfb8aa3b, v90
	v_mul_f32_e32 v97, 0xbfb8aa3b, v91
	v_exp_f32_e32 v96, v96
	v_exp_f32_e32 v97, v97
	v_rcp_f32_e32 v94, v94
	v_rcp_f32_e32 v95, v95
	v_add_f32_e32 v96, 1.0, v96
	v_add_f32_e32 v97, 1.0, v97
	v_rcp_f32_e32 v96, v96
	v_rcp_f32_e32 v97, v97
	v_pk_mul_f32 v[88:89], v[88:89], v[94:95]
	v_pk_mul_f32 v[86:87], v[86:87], v[92:93]
	v_pk_mul_f32 v[88:89], v[80:81], v[88:89]
	v_pk_mul_f32 v[80:81], v[90:91], v[96:97]
	s_nop 0
	v_pk_mul_f32 v[90:91], v[82:83], v[80:81]
	v_cvt_pk_bf16_f32 v80, v84, v85
	v_mul_f32_e32 v84, 0xbfb8aa3b, v76
	v_cvt_pk_bf16_f32 v81, v86, v87
	v_exp_f32_e32 v86, v84
	v_mul_f32_e32 v84, 0xbfb8aa3b, v77
	v_exp_f32_e32 v87, v84
	v_mad_i64_i32 v[84:85], s[4:5], v98, s6, v[112:113]
	v_cvt_pk_bf16_f32 v82, v88, v89
	v_cvt_pk_bf16_f32 v83, v90, v91
	v_add_f32_e32 v86, 1.0, v86
	v_add_f32_e32 v87, 1.0, v87
	v_lshl_add_u64 v[84:85], v[84:85], 0, v[114:115]
	v_rcp_f32_e32 v86, v86
	v_rcp_f32_e32 v87, v87
	global_store_dwordx4 v[84:85], v[80:83], off
	v_pk_mul_f32 v[76:77], v[76:77], v[86:87]
	s_nop 0
	v_mul_f32_e32 v80, 0xbfb8aa3b, v78
	v_mul_f32_e32 v81, 0xbfb8aa3b, v79
	v_exp_f32_e32 v80, v80
	v_exp_f32_e32 v81, v81
	v_pk_mul_f32 v[68:69], v[68:69], v[76:77]
	v_or_b32_e32 v82, 48, v132
	v_add_f32_e32 v76, 1.0, v80
	v_add_f32_e32 v77, 1.0, v81
	v_mul_f32_e32 v80, 0xbfb8aa3b, v72
	v_mul_f32_e32 v81, 0xbfb8aa3b, v73
	v_rcp_f32_e32 v76, v76
	v_rcp_f32_e32 v77, v77
	v_exp_f32_e32 v80, v80
	v_exp_f32_e32 v81, v81
	v_pk_mul_f32 v[76:77], v[78:79], v[76:77]
	v_add_f32_e32 v78, 1.0, v80
	v_add_f32_e32 v79, 1.0, v81
	v_mul_f32_e32 v80, 0xbfb8aa3b, v74
	v_mul_f32_e32 v81, 0xbfb8aa3b, v75
	v_exp_f32_e32 v80, v80
	v_exp_f32_e32 v81, v81
	v_rcp_f32_e32 v78, v78
	v_rcp_f32_e32 v79, v79
	v_add_f32_e32 v80, 1.0, v80
	v_add_f32_e32 v81, 1.0, v81
	v_rcp_f32_e32 v80, v80
	v_rcp_f32_e32 v81, v81
	v_pk_mul_f32 v[72:73], v[72:73], v[78:79]
	v_pk_mul_f32 v[70:71], v[70:71], v[76:77]
	v_pk_mul_f32 v[72:73], v[64:65], v[72:73]
	v_pk_mul_f32 v[64:65], v[74:75], v[80:81]
	s_nop 0
	v_pk_mul_f32 v[74:75], v[66:67], v[64:65]
	v_cvt_pk_bf16_f32 v64, v68, v69
	v_mul_f32_e32 v68, 0xbfb8aa3b, v60
	v_cvt_pk_bf16_f32 v65, v70, v71
	v_exp_f32_e32 v70, v68
	v_mul_f32_e32 v68, 0xbfb8aa3b, v61
	v_exp_f32_e32 v71, v68
	v_mad_i64_i32 v[68:69], s[4:5], v82, s6, v[112:113]
	v_cvt_pk_bf16_f32 v66, v72, v73
	v_cvt_pk_bf16_f32 v67, v74, v75
	v_add_f32_e32 v70, 1.0, v70
	v_add_f32_e32 v71, 1.0, v71
	v_lshl_add_u64 v[68:69], v[68:69], 0, v[114:115]
	v_rcp_f32_e32 v70, v70
	v_rcp_f32_e32 v71, v71
	global_store_dwordx4 v[68:69], v[64:67], off
	v_cmp_eq_u32_e64 s[98:99], 1, v160
	s_nop 1
	s_mov_b64 exec, s[98:99]
	v_pk_mul_f32 v[60:61], v[60:61], v[70:71]
	s_nop 0
	v_mul_f32_e32 v64, 0xbfb8aa3b, v62
	v_mul_f32_e32 v65, 0xbfb8aa3b, v63
	v_exp_f32_e32 v64, v64
	v_exp_f32_e32 v65, v65
	v_pk_mul_f32 v[52:53], v[52:53], v[60:61]
	v_add_u32_e32 v66, s0, v205
	v_add_f32_e32 v60, 1.0, v64
	v_add_f32_e32 v61, 1.0, v65
	v_mul_f32_e32 v64, 0xbfb8aa3b, v56
	v_mul_f32_e32 v65, 0xbfb8aa3b, v57
	v_rcp_f32_e32 v60, v60
	v_rcp_f32_e32 v61, v61
	v_exp_f32_e32 v64, v64
	v_exp_f32_e32 v65, v65
	v_pk_mul_f32 v[60:61], v[62:63], v[60:61]
	v_add_f32_e32 v62, 1.0, v64
	v_add_f32_e32 v63, 1.0, v65
	v_mul_f32_e32 v64, 0xbfb8aa3b, v58
	v_mul_f32_e32 v65, 0xbfb8aa3b, v59
	v_exp_f32_e32 v64, v64
	v_exp_f32_e32 v65, v65
	v_rcp_f32_e32 v62, v62
	v_rcp_f32_e32 v63, v63
	v_add_f32_e32 v64, 1.0, v64
	v_add_f32_e32 v65, 1.0, v65
	v_rcp_f32_e32 v64, v64
	v_rcp_f32_e32 v65, v65
	v_pk_mul_f32 v[56:57], v[56:57], v[62:63]
	v_pk_mul_f32 v[54:55], v[54:55], v[60:61]
	v_pk_mul_f32 v[56:57], v[48:49], v[56:57]
	v_pk_mul_f32 v[48:49], v[58:59], v[64:65]
	s_nop 0
	v_pk_mul_f32 v[58:59], v[50:51], v[48:49]
	v_cvt_pk_bf16_f32 v48, v52, v53
	v_mul_f32_e32 v52, 0xbfb8aa3b, v44
	v_cvt_pk_bf16_f32 v49, v54, v55
	v_exp_f32_e32 v54, v52
	v_mul_f32_e32 v52, 0xbfb8aa3b, v45
	v_exp_f32_e32 v55, v52
	v_mad_i64_i32 v[52:53], s[0:1], v66, s6, v[112:113]
	v_cvt_pk_bf16_f32 v50, v56, v57
	v_cvt_pk_bf16_f32 v51, v58, v59
	v_add_f32_e32 v54, 1.0, v54
	v_add_f32_e32 v55, 1.0, v55
	v_lshl_add_u64 v[52:53], v[52:53], 0, v[114:115]
	v_rcp_f32_e32 v54, v54
	v_rcp_f32_e32 v55, v55
	global_store_dwordx4 v[52:53], v[48:51], off
	v_pk_mul_f32 v[44:45], v[44:45], v[54:55]
	s_nop 0
	v_mul_f32_e32 v48, 0xbfb8aa3b, v46
	v_mul_f32_e32 v49, 0xbfb8aa3b, v47
	v_exp_f32_e32 v48, v48
	v_exp_f32_e32 v49, v49
	v_pk_mul_f32 v[36:37], v[36:37], v[44:45]
	v_or_b32_e32 v50, 16, v66
	v_add_f32_e32 v44, 1.0, v48
	v_add_f32_e32 v45, 1.0, v49
	v_mul_f32_e32 v48, 0xbfb8aa3b, v40
	v_mul_f32_e32 v49, 0xbfb8aa3b, v41
	v_rcp_f32_e32 v44, v44
	v_rcp_f32_e32 v45, v45
	v_exp_f32_e32 v48, v48
	v_exp_f32_e32 v49, v49
	v_pk_mul_f32 v[44:45], v[46:47], v[44:45]
	v_add_f32_e32 v46, 1.0, v48
	v_add_f32_e32 v47, 1.0, v49
	v_mul_f32_e32 v48, 0xbfb8aa3b, v42
	v_mul_f32_e32 v49, 0xbfb8aa3b, v43
	v_exp_f32_e32 v48, v48
	v_exp_f32_e32 v49, v49
	v_rcp_f32_e32 v46, v46
	v_rcp_f32_e32 v47, v47
	v_add_f32_e32 v48, 1.0, v48
	v_add_f32_e32 v49, 1.0, v49
	v_rcp_f32_e32 v48, v48
	v_rcp_f32_e32 v49, v49
	v_pk_mul_f32 v[40:41], v[40:41], v[46:47]
	v_pk_mul_f32 v[38:39], v[38:39], v[44:45]
	v_pk_mul_f32 v[40:41], v[32:33], v[40:41]
	v_pk_mul_f32 v[32:33], v[42:43], v[48:49]
	s_nop 0
	v_pk_mul_f32 v[42:43], v[34:35], v[32:33]
	v_cvt_pk_bf16_f32 v32, v36, v37
	v_mul_f32_e32 v36, 0xbfb8aa3b, v28
	v_cvt_pk_bf16_f32 v33, v38, v39
	v_exp_f32_e32 v38, v36
	v_mul_f32_e32 v36, 0xbfb8aa3b, v29
	v_exp_f32_e32 v39, v36
	v_mad_i64_i32 v[36:37], s[0:1], v50, s6, v[112:113]
	v_cvt_pk_bf16_f32 v34, v40, v41
	v_cvt_pk_bf16_f32 v35, v42, v43
	v_add_f32_e32 v38, 1.0, v38
	v_add_f32_e32 v39, 1.0, v39
	v_lshl_add_u64 v[36:37], v[36:37], 0, v[114:115]
	v_rcp_f32_e32 v38, v38
	v_rcp_f32_e32 v39, v39
	global_store_dwordx4 v[36:37], v[32:35], off
	v_pk_mul_f32 v[28:29], v[28:29], v[38:39]
	s_nop 0
	v_mul_f32_e32 v32, 0xbfb8aa3b, v30
	v_mul_f32_e32 v33, 0xbfb8aa3b, v31
	v_exp_f32_e32 v32, v32
	v_exp_f32_e32 v33, v33
	v_pk_mul_f32 v[20:21], v[20:21], v[28:29]
	v_or_b32_e32 v34, 32, v66
	v_add_f32_e32 v28, 1.0, v32
	v_add_f32_e32 v29, 1.0, v33
	v_mul_f32_e32 v32, 0xbfb8aa3b, v24
	v_mul_f32_e32 v33, 0xbfb8aa3b, v25
	v_rcp_f32_e32 v28, v28
	v_rcp_f32_e32 v29, v29
	v_exp_f32_e32 v32, v32
	v_exp_f32_e32 v33, v33
	v_pk_mul_f32 v[28:29], v[30:31], v[28:29]
	v_add_f32_e32 v30, 1.0, v32
	v_add_f32_e32 v31, 1.0, v33
	v_mul_f32_e32 v32, 0xbfb8aa3b, v26
	v_mul_f32_e32 v33, 0xbfb8aa3b, v27
	v_exp_f32_e32 v32, v32
	v_exp_f32_e32 v33, v33
	v_rcp_f32_e32 v30, v30
	v_rcp_f32_e32 v31, v31
	v_add_f32_e32 v32, 1.0, v32
	v_add_f32_e32 v33, 1.0, v33
	v_rcp_f32_e32 v32, v32
	v_rcp_f32_e32 v33, v33
	v_pk_mul_f32 v[24:25], v[24:25], v[30:31]
	v_pk_mul_f32 v[22:23], v[22:23], v[28:29]
	v_pk_mul_f32 v[24:25], v[16:17], v[24:25]
	v_pk_mul_f32 v[16:17], v[26:27], v[32:33]
	s_nop 0
	v_pk_mul_f32 v[26:27], v[18:19], v[16:17]
	v_cvt_pk_bf16_f32 v16, v20, v21
	v_mul_f32_e32 v20, 0xbfb8aa3b, v12
	v_cvt_pk_bf16_f32 v17, v22, v23
	v_exp_f32_e32 v22, v20
	v_mul_f32_e32 v20, 0xbfb8aa3b, v13
	v_exp_f32_e32 v23, v20
	v_mad_i64_i32 v[20:21], s[0:1], v34, s6, v[112:113]
	v_cvt_pk_bf16_f32 v18, v24, v25
	v_cvt_pk_bf16_f32 v19, v26, v27
	v_add_f32_e32 v22, 1.0, v22
	v_add_f32_e32 v23, 1.0, v23
	v_lshl_add_u64 v[20:21], v[20:21], 0, v[114:115]
	v_rcp_f32_e32 v22, v22
	v_rcp_f32_e32 v23, v23
	global_store_dwordx4 v[20:21], v[16:19], off
	v_pk_mul_f32 v[12:13], v[12:13], v[22:23]
	s_nop 0
	v_mul_f32_e32 v16, 0xbfb8aa3b, v14
	v_mul_f32_e32 v17, 0xbfb8aa3b, v15
	v_exp_f32_e32 v16, v16
	v_exp_f32_e32 v17, v17
	v_pk_mul_f32 v[4:5], v[4:5], v[12:13]
	v_or_b32_e32 v18, 48, v66
	v_add_f32_e32 v12, 1.0, v16
	v_add_f32_e32 v13, 1.0, v17
	v_mul_f32_e32 v16, 0xbfb8aa3b, v8
	v_mul_f32_e32 v17, 0xbfb8aa3b, v9
	v_rcp_f32_e32 v12, v12
	v_rcp_f32_e32 v13, v13
	v_exp_f32_e32 v16, v16
	v_exp_f32_e32 v17, v17
	v_pk_mul_f32 v[12:13], v[14:15], v[12:13]
	v_add_f32_e32 v14, 1.0, v16
	v_add_f32_e32 v15, 1.0, v17
	v_mul_f32_e32 v16, 0xbfb8aa3b, v10
	v_mul_f32_e32 v17, 0xbfb8aa3b, v11
	v_exp_f32_e32 v16, v16
	v_exp_f32_e32 v17, v17
	v_rcp_f32_e32 v14, v14
	v_rcp_f32_e32 v15, v15
	v_add_f32_e32 v16, 1.0, v16
	v_add_f32_e32 v17, 1.0, v17
	v_rcp_f32_e32 v16, v16
	v_rcp_f32_e32 v17, v17
	v_pk_mul_f32 v[8:9], v[8:9], v[14:15]
	v_pk_mul_f32 v[6:7], v[6:7], v[12:13]
	v_pk_mul_f32 v[8:9], v[0:1], v[8:9]
	v_pk_mul_f32 v[0:1], v[10:11], v[16:17]
	s_nop 0
	v_pk_mul_f32 v[10:11], v[2:3], v[0:1]
	v_cvt_pk_bf16_f32 v0, v4, v5
	v_mad_i64_i32 v[4:5], s[0:1], v18, s6, v[112:113]
	v_cvt_pk_bf16_f32 v1, v6, v7
	v_cvt_pk_bf16_f32 v2, v8, v9
	v_cvt_pk_bf16_f32 v3, v10, v11
	v_lshl_add_u64 v[4:5], v[4:5], 0, v[114:115]
	s_mov_b64 s[0:1], -1
	global_store_dwordx4 v[4:5], v[0:3], off
	s_mov_b64 exec, -1
	s_cbranch_vccnz .LBB0_38
	v_readlane_b32 s0, v255, 30
	v_readlane_b32 s1, v255, 31
	s_andn2_b64 vcc, exec, s[0:1]
	s_cbranch_vccnz .LBB0_37
	s_barrier
	s_branch .LBB0_37
